# version 97 plus sample-row GEMM loops: the last iteration does not issue its eight unused (clamped) global loads
# baseline (speedup 1.0000x reference)
; #define LAS __attribute__((address_space(3)))
; #define LDS_BARRIER() asm volatile("s_waitcnt lgkmcnt(0)\n\ts_barrier" ::: "memory")
; __device__ __forceinline__ void srg_phase(LAS unsigned char* L, const bf16* Aop, const bf16* Bt, const int K, bf16* xb, float* rowss, const float scale, const bool fin, const int G, const int tid) {
;     ...
;         for (int t = 0; t < nt; t += 2) {
; #pragma unroll
;             for (int i = 0; i < 2; ++i) {
;                 LAS unsigned char* wb_ = wr0 + i * 34816;
;                 *(LAS v4u*)(wb_) = ra[i][0]; *(LAS v4u*)(wb_ + 128) = ra[i][1]; *(LAS v4u*)(wb_ + 17408) = rb[i][0]; *(LAS v4u*)(wb_ + 17408 + 128) = rb[i][1];
;                 { const int tn2 = (t + 2 + i < nt) ? t + 2 + i : i; const bf16* a2 = ag + (size_t)tn2 * 128; const bf16* b2 = bg + (size_t)tn2 * 128;
;                   ra[i][0] = *(const v4u*)a2; ra[i][1] = *(const v4u*)(a2 + 64); rb[i][0] = *(const v4u*)b2; rb[i][1] = *(const v4u*)(b2 + 64); }
;                 LDS_BARRIER();
; #pragma unroll
;                 for (int ks = 0; ks < 4; ++ks) {
;                     const bf16x8 af = frag16(fa + i * 34816 + ks * 64), b0 = frag16(fb + i * 34816 + ks * 64), b1 = frag16(fb + i * 34816 + 16 * 272 + ks * 64);
;                     acc0 = MFMA16(b0, af, acc0); acc1 = MFMA16(b1, af, acc1);
;                 }
;             }
;         }
;         {
;             const int row = MP + 64 * tm + 16 * wm + r16, col0 = 64 * tn + 32 * wn + 4 * q;
;             bf16* px = xb + (size_t)row * D + col0;
;             const v2u xa = *(const v2u*)px, xc = *(const v2u*)(px + 16);
;             const float a0 = __builtin_bit_cast(float, xa.x << 16) + acc0[0] * scale, a1 = __builtin_bit_cast(float, xa.x & 0xffff0000u) + acc0[1] * scale, a2 = __builtin_bit_cast(float, xa.y << 16) + acc0[2] * scale, a3 = __builtin_bit_cast(float, xa.y & 0xffff0000u) + acc0[3] * scale;
;             const float b0 = __builtin_bit_cast(float, xc.x << 16) + acc1[0] * scale, b1 = __builtin_bit_cast(float, xc.x & 0xffff0000u) + acc1[1] * scale, b2 = __builtin_bit_cast(float, xc.y << 16) + acc1[2] * scale, b3 = __builtin_bit_cast(float, xc.y & 0xffff0000u) + acc1[3] * scale;
;             v2u wa, wb; wa.x = cvtpk(a0, a1); wa.y = cvtpk(a2, a3); wb.x = cvtpk(b0, b1); wb.y = cvtpk(b2, b3);
;             *(v2u*)px = wa; *(v2u*)(px + 16) = wb;
;             float ss = 0.f;
; #pragma unroll
.LBB0_139:
	s_add_i32 s13, s12, -1
	s_cmp_lt_u32 s13, s10
	s_cselect_b64 s[14:15], -1, 0
	s_and_b64 vcc, s[14:15], exec
	s_cselect_b32 s62, s13, 0
	s_lshl_b64 s[14:15], s[62:63], 8
	s_waitcnt vmcnt(3)
	ds_write_b128 v56, v[18:21]
	s_waitcnt vmcnt(2)
	ds_write_b128 v56, v[14:17] offset:128
	ds_write_b128 v56, v[10:13] offset:17408
	ds_write_b128 v56, v[6:9] offset:17536
	s_cbranch_vccz .Lska_0
	v_lshl_add_u64 v[6:7], v[50:51], 0, s[14:15]
	v_lshl_add_u64 v[8:9], v[52:53], 0, s[14:15]
	global_load_dwordx4 v[18:21], v[6:7], off
	global_load_dwordx4 v[14:17], v[6:7], off offset:128
	global_load_dwordx4 v[10:13], v[8:9], off
	s_nop 0
	global_load_dwordx4 v[6:9], v[8:9], off offset:128
.Lska_0:
	s_waitcnt lgkmcnt(0)
	s_barrier
	ds_read_b128 v[60:63], v57
	ds_read_b128 v[64:67], v58 offset:17408
	ds_read_b128 v[68:71], v58 offset:21760
	s_waitcnt lgkmcnt(1)
	v_mfma_f32_16x16x32_bf16 v[38:41], v[64:67], v[60:63], v[38:41]
	s_cmp_lt_u32 s12, s10
	s_cselect_b32 s62, s12, 1
	s_lshl_b64 s[14:15], s[62:63], 8
	s_waitcnt lgkmcnt(0)
	v_mfma_f32_16x16x32_bf16 v[42:45], v[68:71], v[60:63], v[42:45]
	ds_read_b128 v[60:63], v57 offset:64
	ds_read_b128 v[64:67], v58 offset:17472
	ds_read_b128 v[68:71], v58 offset:21824
	s_add_i32 s12, s12, 2
	s_waitcnt lgkmcnt(1)
	v_mfma_f32_16x16x32_bf16 v[38:41], v[64:67], v[60:63], v[38:41]
	s_waitcnt lgkmcnt(0)
	v_mfma_f32_16x16x32_bf16 v[42:45], v[68:71], v[60:63], v[42:45]
	ds_read_b128 v[60:63], v57 offset:128
	ds_read_b128 v[64:67], v58 offset:17536
	ds_read_b128 v[68:71], v58 offset:21888
	s_waitcnt lgkmcnt(1)
	v_mfma_f32_16x16x32_bf16 v[38:41], v[64:67], v[60:63], v[38:41]
	s_waitcnt lgkmcnt(0)
	v_mfma_f32_16x16x32_bf16 v[42:45], v[68:71], v[60:63], v[42:45]
	ds_read_b128 v[60:63], v57 offset:192
	ds_read_b128 v[64:67], v58 offset:17600
	ds_read_b128 v[68:71], v58 offset:21952
	s_cbranch_vccz .Lska_1
	s_waitcnt vmcnt(5)
	ds_write_b128 v56, v[26:29] offset:34816
	s_waitcnt vmcnt(4)
	ds_write_b128 v56, v[30:33] offset:34944
	ds_write_b128 v56, v[22:25] offset:52224
	ds_write_b128 v56, v[34:37] offset:52352
	v_lshl_add_u64 v[22:23], v[50:51], 0, s[14:15]
	v_lshl_add_u64 v[34:35], v[52:53], 0, s[14:15]
	global_load_dwordx4 v[26:29], v[22:23], off
	global_load_dwordx4 v[30:33], v[22:23], off offset:128
	s_nop 0
	global_load_dwordx4 v[22:25], v[34:35], off
	s_nop 0
	global_load_dwordx4 v[34:37], v[34:35], off offset:128
	s_branch .Lska_2
.Lska_1:
	s_waitcnt vmcnt(0)
	ds_write_b128 v56, v[26:29] offset:34816
	ds_write_b128 v56, v[30:33] offset:34944
	ds_write_b128 v56, v[22:25] offset:52224
	ds_write_b128 v56, v[34:37] offset:52352
.Lska_2:
	s_waitcnt lgkmcnt(0)
	s_barrier
	s_waitcnt lgkmcnt(5)
	v_mfma_f32_16x16x32_bf16 v[38:41], v[64:67], v[60:63], v[38:41]
	s_waitcnt lgkmcnt(4)
	v_mfma_f32_16x16x32_bf16 v[42:45], v[68:71], v[60:63], v[42:45]
	ds_read_b128 v[60:63], v57 offset:34816
	ds_read_b128 v[64:67], v58 offset:52224
	ds_read_b128 v[68:71], v58 offset:56576
	s_waitcnt lgkmcnt(1)
	v_mfma_f32_16x16x32_bf16 v[38:41], v[64:67], v[60:63], v[38:41]
	s_waitcnt lgkmcnt(0)
	v_mfma_f32_16x16x32_bf16 v[42:45], v[68:71], v[60:63], v[42:45]
	ds_read_b128 v[60:63], v57 offset:34880
	ds_read_b128 v[64:67], v58 offset:52288
	ds_read_b128 v[68:71], v58 offset:56640
	s_waitcnt lgkmcnt(1)
	v_mfma_f32_16x16x32_bf16 v[38:41], v[64:67], v[60:63], v[38:41]
	s_waitcnt lgkmcnt(0)
	v_mfma_f32_16x16x32_bf16 v[42:45], v[68:71], v[60:63], v[42:45]
	ds_read_b128 v[60:63], v57 offset:34944
	ds_read_b128 v[64:67], v58 offset:52352
	ds_read_b128 v[68:71], v58 offset:56704
	s_waitcnt lgkmcnt(1)
	v_mfma_f32_16x16x32_bf16 v[38:41], v[64:67], v[60:63], v[38:41]
	s_waitcnt lgkmcnt(0)
	v_mfma_f32_16x16x32_bf16 v[42:45], v[68:71], v[60:63], v[42:45]
	ds_read_b128 v[60:63], v57 offset:35008
	ds_read_b128 v[64:67], v58 offset:52416
	ds_read_b128 v[68:71], v58 offset:56768
	s_waitcnt lgkmcnt(1)
	v_mfma_f32_16x16x32_bf16 v[38:41], v[64:67], v[60:63], v[38:41]
	s_waitcnt lgkmcnt(0)
	v_mfma_f32_16x16x32_bf16 v[42:45], v[68:71], v[60:63], v[42:45]
	s_cbranch_vccnz .LBB0_139
	s_waitcnt vmcnt(4)
	v_add_u32_e32 v6, s0, v54
	v_ashrrev_i32_e32 v7, 31, v6
	v_or_b32_e32 v10, s1, v55
	v_lshlrev_b64 v[8:9], 11, v[6:7]
	v_lshl_add_u64 v[8:9], s[84:85], 0, v[8:9]
	v_lshlrev_b32_e32 v10, 1, v10
	v_mov_b32_e32 v11, v4
	v_lshl_add_u64 v[8:9], v[8:9], 0, v[10:11]
	global_load_dwordx2 v[10:11], v[8:9], off
	global_load_dwordx2 v[12:13], v[8:9], off offset:32
	s_waitcnt vmcnt(1)
	v_lshlrev_b32_e32 v14, 16, v10
	v_and_b32_e32 v15, 0xffff0000, v10
	v_lshlrev_b32_e32 v10, 16, v11
	v_and_b32_e32 v11, 0xffff0000, v11
	v_pk_fma_f32 v[14:15], v[2:3], v[38:39], v[14:15]
	v_pk_fma_f32 v[10:11], v[2:3], v[40:41], v[10:11]
	s_waitcnt vmcnt(0)
	v_lshlrev_b32_e32 v16, 16, v12
	v_and_b32_e32 v17, 0xffff0000, v12
	v_lshlrev_b32_e32 v12, 16, v13
	v_and_b32_e32 v13, 0xffff0000, v13
	v_pk_fma_f32 v[16:17], v[2:3], v[42:43], v[16:17]
	v_pk_fma_f32 v[12:13], v[2:3], v[44:45], v[12:13]
	v_cvt_pk_bf16_f32 v14, v14, v15
	v_cvt_pk_bf16_f32 v15, v10, v11
	v_cvt_pk_bf16_f32 v10, v16, v17
	v_cvt_pk_bf16_f32 v11, v12, v13
	global_store_dwordx2 v[8:9], v[14:15], off
	global_store_dwordx2 v[8:9], v[10:11], off offset:32
	v_and_b32_e32 v9, 0xffff0000, v14
	v_lshlrev_b32_e32 v8, 16, v14
	v_lshlrev_b32_e32 v12, 16, v10
	v_and_b32_e32 v10, 0xffff0000, v10
	v_mul_f32_e32 v9, v9, v9
	v_fmac_f32_e32 v9, v8, v8
	v_mul_f32_e32 v8, v10, v10
	v_fmac_f32_e32 v8, v12, v12
	v_and_b32_e32 v10, 0xffff0000, v15
	v_add_f32_e32 v8, v9, v8
	v_lshlrev_b32_e32 v9, 16, v15
	v_lshlrev_b32_e32 v12, 16, v11
	v_and_b32_e32 v11, 0xffff0000, v11
	v_mul_f32_e32 v10, v10, v10
	v_fmac_f32_e32 v10, v9, v9
	v_mul_f32_e32 v9, v11, v11
	v_fmac_f32_e32 v9, v12, v12
	v_add_f32_e32 v9, v10, v9
	v_and_b32_e32 v10, 64, v232
	v_add_f32_e32 v8, v8, v9
	v_xor_b32_e32 v9, 16, v232
	v_add_u32_e32 v10, 64, v10
	v_cmp_lt_i32_e32 vcc, v9, v10
	s_nop 1
	v_cndmask_b32_e32 v9, v232, v9, vcc
	v_lshlrev_b32_e32 v9, 2, v9
	ds_bpermute_b32 v9, v9, v8
	s_waitcnt lgkmcnt(0)
	v_add_f32_e32 v8, v8, v9
	v_xor_b32_e32 v9, 32, v232
	v_cmp_lt_i32_e32 vcc, v9, v10
	s_nop 1
	v_cndmask_b32_e32 v9, v232, v9, vcc
	v_lshlrev_b32_e32 v9, 2, v9
	ds_bpermute_b32 v9, v9, v8
	s_and_saveexec_b64 s[0:1], s[38:39]
	s_cbranch_execz .LBB0_137
	s_waitcnt lgkmcnt(0)
	v_add_f32_e32 v8, v8, v9
	v_lshl_add_u64 v[6:7], v[6:7], 2, s[8:9]
	global_atomic_add_f32 v[6:7], v8, off
	s_branch .LBB0_137

; #define LAS __attribute__((address_space(3)))
; #define LDS_BARRIER() asm volatile("s_waitcnt lgkmcnt(0)\n\ts_barrier" ::: "memory")
; __device__ __forceinline__ void srg_phase(LAS unsigned char* L, const bf16* Aop, const bf16* Bt, const int K, bf16* xb, float* rowss, const float scale, const bool fin, const int G, const int tid) {
;     ...
;         for (int i = 0; i < 2; ++i) { ra[i][0] = *(const v4u*)(ag + i * 128); ra[i][1] = *(const v4u*)(ag + i * 128 + 64); rb[i][0] = *(const v4u*)(bg + i * 128); rb[i][1] = *(const v4u*)(bg + i * 128 + 64); }
;         LAS unsigned char* wr0 = L + lr * 272 + lc * 2;
;         const LAS unsigned char* fa = L + (16 * wm + r16) * 272 + (8 * q) * 2;
;         const LAS unsigned char* fb = L + 17408 + (32 * wn + r16) * 272 + (8 * q) * 2;
; #pragma unroll 1
;         for (int t = 0; t < nt; t += 2) {
; #pragma unroll
;             for (int i = 0; i < 2; ++i) {
;                 LAS unsigned char* wb_ = wr0 + i * 34816;
;                 *(LAS v4u*)(wb_) = ra[i][0]; *(LAS v4u*)(wb_ + 128) = ra[i][1]; *(LAS v4u*)(wb_ + 17408) = rb[i][0]; *(LAS v4u*)(wb_ + 17408 + 128) = rb[i][1];
;                 { const int tn2 = (t + 2 + i < nt) ? t + 2 + i : i; const bf16* a2 = ag + (size_t)tn2 * 128; const bf16* b2 = bg + (size_t)tn2 * 128;
;                   ra[i][0] = *(const v4u*)a2; ra[i][1] = *(const v4u*)(a2 + 64); rb[i][0] = *(const v4u*)b2; rb[i][1] = *(const v4u*)(b2 + 64); }
;                 LDS_BARRIER();
; #pragma unroll
;                 for (int ks = 0; ks < 4; ++ks) {
;                     const bf16x8 af = frag16(fa + i * 34816 + ks * 64), b0 = frag16(fb + i * 34816 + ks * 64), b1 = frag16(fb + i * 34816 + 16 * 272 + ks * 64);
;                     acc0 = MFMA16(b0, af, acc0); acc1 = MFMA16(b1, af, acc1);
;                 }
;             }
;         }
;         {
;             const int row = MP + 64 * tm + 16 * wm + r16, col0 = 64 * tn + 32 * wn + 4 * q;
;             bf16* px = xb + (size_t)row * D + col0;
;             const v2u xa = *(const v2u*)px, xc = *(const v2u*)(px + 16);
;             const float a0 = __builtin_bit_cast(float, xa.x << 16) + acc0[0] * scale, a1 = __builtin_bit_cast(float, xa.x & 0xffff0000u) + acc0[1] * scale, a2 = __builtin_bit_cast(float, xa.y << 16) + acc0[2] * scale, a3 = __builtin_bit_cast(float, xa.y & 0xffff0000u) + acc0[3] * scale;
.LBB0_193:
	s_add_i32 s13, s12, -1
	s_cmp_lt_u32 s13, s10
	s_cselect_b64 s[14:15], -1, 0
	s_and_b64 vcc, s[14:15], exec
	s_cselect_b32 s62, s13, 0
	s_lshl_b64 s[14:15], s[62:63], 8
	s_waitcnt vmcnt(3)
	ds_write_b128 v57, v[18:21]
	s_waitcnt vmcnt(2)
	ds_write_b128 v57, v[14:17] offset:128
	ds_write_b128 v57, v[10:13] offset:17408
	ds_write_b128 v57, v[6:9] offset:17536
	s_cbranch_vccz .Lskb_0
	v_lshl_add_u64 v[6:7], v[50:51], 0, s[14:15]
	v_lshl_add_u64 v[8:9], v[52:53], 0, s[14:15]
	global_load_dwordx4 v[18:21], v[6:7], off
	global_load_dwordx4 v[14:17], v[6:7], off offset:128
	global_load_dwordx4 v[10:13], v[8:9], off
	s_nop 0
	global_load_dwordx4 v[6:9], v[8:9], off offset:128
.Lskb_0:
	s_waitcnt lgkmcnt(0)
	s_barrier
	ds_read_b128 v[60:63], v58
	ds_read_b128 v[64:67], v5 offset:17408
	ds_read_b128 v[68:71], v5 offset:21760
	s_waitcnt lgkmcnt(1)
	v_mfma_f32_16x16x32_bf16 v[38:41], v[64:67], v[60:63], v[38:41]
	s_cmp_lt_u32 s12, s10
	s_cselect_b32 s62, s12, 1
	s_lshl_b64 s[14:15], s[62:63], 8
	s_waitcnt lgkmcnt(0)
	v_mfma_f32_16x16x32_bf16 v[42:45], v[68:71], v[60:63], v[42:45]
	ds_read_b128 v[60:63], v58 offset:64
	ds_read_b128 v[64:67], v5 offset:17472
	ds_read_b128 v[68:71], v5 offset:21824
	s_add_i32 s12, s12, 2
	s_waitcnt lgkmcnt(1)
	v_mfma_f32_16x16x32_bf16 v[38:41], v[64:67], v[60:63], v[38:41]
	s_waitcnt lgkmcnt(0)
	v_mfma_f32_16x16x32_bf16 v[42:45], v[68:71], v[60:63], v[42:45]
	ds_read_b128 v[60:63], v58 offset:128
	ds_read_b128 v[64:67], v5 offset:17536
	ds_read_b128 v[68:71], v5 offset:21888
	s_waitcnt lgkmcnt(1)
	v_mfma_f32_16x16x32_bf16 v[38:41], v[64:67], v[60:63], v[38:41]
	s_waitcnt lgkmcnt(0)
	v_mfma_f32_16x16x32_bf16 v[42:45], v[68:71], v[60:63], v[42:45]
	ds_read_b128 v[60:63], v58 offset:192
	ds_read_b128 v[64:67], v5 offset:17600
	ds_read_b128 v[68:71], v5 offset:21952
	s_cbranch_vccz .Lskb_1
	s_waitcnt vmcnt(5)
	ds_write_b128 v57, v[26:29] offset:34816
	s_waitcnt vmcnt(4)
	ds_write_b128 v57, v[30:33] offset:34944
	ds_write_b128 v57, v[22:25] offset:52224
	ds_write_b128 v57, v[34:37] offset:52352
	v_lshl_add_u64 v[22:23], v[50:51], 0, s[14:15]
	v_lshl_add_u64 v[34:35], v[52:53], 0, s[14:15]
	global_load_dwordx4 v[26:29], v[22:23], off
	global_load_dwordx4 v[30:33], v[22:23], off offset:128
	s_nop 0
	global_load_dwordx4 v[22:25], v[34:35], off
	s_nop 0
	global_load_dwordx4 v[34:37], v[34:35], off offset:128
	s_branch .Lskb_2
.Lskb_1:
	s_waitcnt vmcnt(0)
	ds_write_b128 v57, v[26:29] offset:34816
	ds_write_b128 v57, v[30:33] offset:34944
	ds_write_b128 v57, v[22:25] offset:52224
	ds_write_b128 v57, v[34:37] offset:52352
.Lskb_2:
	s_waitcnt lgkmcnt(0)
	s_barrier
	s_waitcnt lgkmcnt(5)
	v_mfma_f32_16x16x32_bf16 v[38:41], v[64:67], v[60:63], v[38:41]
	s_waitcnt lgkmcnt(4)
	v_mfma_f32_16x16x32_bf16 v[42:45], v[68:71], v[60:63], v[42:45]
	ds_read_b128 v[60:63], v58 offset:34816
	ds_read_b128 v[64:67], v5 offset:52224
	ds_read_b128 v[68:71], v5 offset:56576
	s_waitcnt lgkmcnt(1)
	v_mfma_f32_16x16x32_bf16 v[38:41], v[64:67], v[60:63], v[38:41]
	s_waitcnt lgkmcnt(0)
	v_mfma_f32_16x16x32_bf16 v[42:45], v[68:71], v[60:63], v[42:45]
	ds_read_b128 v[60:63], v58 offset:34880
	ds_read_b128 v[64:67], v5 offset:52288
	ds_read_b128 v[68:71], v5 offset:56640
	s_waitcnt lgkmcnt(1)
	v_mfma_f32_16x16x32_bf16 v[38:41], v[64:67], v[60:63], v[38:41]
	s_waitcnt lgkmcnt(0)
	v_mfma_f32_16x16x32_bf16 v[42:45], v[68:71], v[60:63], v[42:45]
	ds_read_b128 v[60:63], v58 offset:34944
	ds_read_b128 v[64:67], v5 offset:52352
	ds_read_b128 v[68:71], v5 offset:56704
	s_waitcnt lgkmcnt(1)
	v_mfma_f32_16x16x32_bf16 v[38:41], v[64:67], v[60:63], v[38:41]
	s_waitcnt lgkmcnt(0)
	v_mfma_f32_16x16x32_bf16 v[42:45], v[68:71], v[60:63], v[42:45]
	ds_read_b128 v[60:63], v58 offset:35008
	ds_read_b128 v[64:67], v5 offset:52416
	ds_read_b128 v[68:71], v5 offset:56768
	s_waitcnt lgkmcnt(1)
	v_mfma_f32_16x16x32_bf16 v[38:41], v[64:67], v[60:63], v[38:41]
	s_waitcnt lgkmcnt(0)
	v_mfma_f32_16x16x32_bf16 v[42:45], v[68:71], v[60:63], v[42:45]
	s_cbranch_vccnz .LBB0_193
	s_waitcnt vmcnt(4)
	v_add_u32_e32 v6, s0, v55
	v_ashrrev_i32_e32 v7, 31, v6
	v_or_b32_e32 v10, s1, v56
	v_lshlrev_b64 v[8:9], 11, v[6:7]
	v_lshl_add_u64 v[8:9], s[84:85], 0, v[8:9]
	v_lshlrev_b32_e32 v10, 1, v10
	v_mov_b32_e32 v11, v4
	v_lshl_add_u64 v[8:9], v[8:9], 0, v[10:11]
	global_load_dwordx2 v[10:11], v[8:9], off
	global_load_dwordx2 v[12:13], v[8:9], off offset:32
	s_waitcnt vmcnt(1)
	v_lshlrev_b32_e32 v14, 16, v10
	v_and_b32_e32 v15, 0xffff0000, v10
	v_lshlrev_b32_e32 v10, 16, v11
	v_and_b32_e32 v11, 0xffff0000, v11
	v_pk_fma_f32 v[14:15], v[2:3], v[38:39], v[14:15]
	v_pk_fma_f32 v[10:11], v[2:3], v[40:41], v[10:11]
	s_waitcnt vmcnt(0)
	v_lshlrev_b32_e32 v16, 16, v12
	v_and_b32_e32 v17, 0xffff0000, v12
	v_lshlrev_b32_e32 v12, 16, v13
	v_and_b32_e32 v13, 0xffff0000, v13
	v_pk_fma_f32 v[16:17], v[2:3], v[42:43], v[16:17]
	v_pk_fma_f32 v[12:13], v[2:3], v[44:45], v[12:13]
	v_cvt_pk_bf16_f32 v14, v14, v15
	v_cvt_pk_bf16_f32 v15, v10, v11
	v_cvt_pk_bf16_f32 v10, v16, v17
	v_cvt_pk_bf16_f32 v11, v12, v13
	global_store_dwordx2 v[8:9], v[14:15], off
	global_store_dwordx2 v[8:9], v[10:11], off offset:32
	v_and_b32_e32 v9, 0xffff0000, v14
	v_lshlrev_b32_e32 v8, 16, v14
	v_lshlrev_b32_e32 v12, 16, v10
	v_and_b32_e32 v10, 0xffff0000, v10
	v_mul_f32_e32 v9, v9, v9
	v_fmac_f32_e32 v9, v8, v8
	v_mul_f32_e32 v8, v10, v10
	v_fmac_f32_e32 v8, v12, v12
	v_and_b32_e32 v10, 0xffff0000, v15
	v_add_f32_e32 v8, v9, v8
	v_lshlrev_b32_e32 v9, 16, v15
	v_lshlrev_b32_e32 v12, 16, v11
	v_and_b32_e32 v11, 0xffff0000, v11
	v_mul_f32_e32 v10, v10, v10
	v_fmac_f32_e32 v10, v9, v9
	v_mul_f32_e32 v9, v11, v11
	v_fmac_f32_e32 v9, v12, v12
	v_add_f32_e32 v9, v10, v9
	v_and_b32_e32 v10, 64, v232
	v_add_f32_e32 v8, v8, v9
	v_xor_b32_e32 v9, 16, v232
	v_add_u32_e32 v10, 64, v10
	v_cmp_lt_i32_e32 vcc, v9, v10
	s_nop 1
	v_cndmask_b32_e32 v9, v232, v9, vcc
	v_lshlrev_b32_e32 v9, 2, v9
	ds_bpermute_b32 v9, v9, v8
	s_waitcnt lgkmcnt(0)
	v_add_f32_e32 v8, v8, v9
	v_xor_b32_e32 v9, 32, v232
	v_cmp_lt_i32_e32 vcc, v9, v10
	s_nop 1
	v_cndmask_b32_e32 v9, v232, v9, vcc
	v_lshlrev_b32_e32 v9, 2, v9
	ds_bpermute_b32 v9, v9, v8
	s_and_saveexec_b64 s[0:1], s[36:37]
	s_cbranch_execz .LBB0_191
	s_waitcnt lgkmcnt(0)
	v_add_f32_e32 v8, v8, v9
	v_lshl_add_u64 v[6:7], v[6:7], 2, s[8:9]
	global_atomic_add_f32 v[6:7], v8, off
	s_branch .LBB0_191
